# PF: final-norm gains preloaded once, 4 lone load round trips and store drains removed
# speedup vs baseline: 1.0378x; 1.0048x over previous
.LBB0_1423:
	v_lshlrev_b32_e32 v24, 2, v4
	v_ashrrev_i32_e32 v25, 31, v24
	v_readlane_b32 s0, v251, 31
	v_lshlrev_b64 v[64:65], 2, v[24:25]
	s_waitcnt lgkmcnt(0)
	v_lshl_add_u64 v[100:101], s[4:5], 0, v[64:65]
	global_load_dwordx4 v[104:107], v[100:101], off
	global_load_dwordx4 v[108:111], v[100:101], off offset:1024
	global_load_dwordx4 v[112:115], v[100:101], off offset:2048
	global_load_dwordx4 v[116:119], v[100:101], off offset:3072
	v_readlane_b32 s1, v251, 32
	v_lshl_add_u64 v[68:69], s[44:45], 0, v[64:65]
	s_lshl_b64 s[10:11], s[0:1], 12
	v_readlane_b32 s0, v251, 35
	v_lshl_add_u64 v[0:1], v[68:69], 0, s[10:11]
	v_readlane_b32 s1, v251, 36
	global_load_dwordx4 v[44:47], v[0:1], off
	global_load_dwordx4 v[32:35], v[0:1], off offset:1024
	global_load_dwordx4 v[8:11], v[0:1], off offset:3072
	global_load_dwordx4 v[12:15], v[0:1], off offset:2048
	s_lshl_b64 s[8:9], s[0:1], 12
	v_lshl_add_u64 v[4:5], v[68:69], 0, s[8:9]
	global_load_dwordx4 v[40:43], v[4:5], off
	global_load_dwordx4 v[28:31], v[4:5], off offset:1024
	global_load_dwordx4 v[0:3], v[4:5], off offset:3072
	global_load_dwordx4 v[16:19], v[4:5], off offset:2048
	v_readlane_b32 s0, v251, 39
	v_readlane_b32 s1, v251, 40
	s_lshl_b64 s[6:7], s[0:1], 12
	v_lshl_add_u64 v[26:27], v[68:69], 0, s[6:7]
	global_load_dwordx4 v[48:51], v[26:27], off
	global_load_dwordx4 v[36:39], v[26:27], off offset:1024
	global_load_dwordx4 v[20:23], v[26:27], off offset:2048
	global_load_dwordx4 v[4:7], v[26:27], off offset:3072
	v_xor_b32_e32 v71, 4, v24
	v_readlane_b32 s0, v251, 43
	v_readlane_b32 s1, v251, 44
	s_lshl_b64 s[12:13], s[0:1], 12
	s_mov_b32 s14, 0xf800000
	s_waitcnt vmcnt(0)
	v_pk_mul_f32 v[26:27], v[46:47], v[46:47]
	v_pk_mul_f32 v[52:53], v[44:45], v[44:45]
	v_pk_mul_f32 v[54:55], v[34:35], v[34:35]
	v_pk_mul_f32 v[56:57], v[32:33], v[32:33]
	v_mul_f32_e32 v58, v13, v13
	v_mul_f32_e32 v60, v15, v15
	v_pk_mul_f32 v[62:63], v[42:43], v[42:43]
	v_pk_mul_f32 v[66:67], v[40:41], v[40:41]
	v_pk_mul_f32 v[72:73], v[30:31], v[30:31]
	v_pk_mul_f32 v[74:75], v[28:29], v[28:29]
	v_pk_mov_b32 v[78:79], v[52:53], v[26:27] op_sel:[1,0]
	v_mov_b32_e32 v53, v27
	v_pk_mov_b32 v[26:27], v[56:57], v[54:55] op_sel:[1,0]
	v_mov_b32_e32 v57, v55
	v_mul_f32_e32 v81, v10, v10
	v_mul_f32_e32 v82, v11, v11
	v_pk_fma_f32 v[54:55], v[12:13], v[12:13], v[58:59] op_sel_hi:[1,1,0]
	v_pk_fma_f32 v[58:59], v[14:15], v[14:15], v[60:61] op_sel_hi:[1,1,0]
	v_pk_mov_b32 v[60:61], v[66:67], v[62:63] op_sel:[1,0]
	v_mov_b32_e32 v67, v63
	v_pk_mov_b32 v[62:63], v[74:75], v[72:73] op_sel:[1,0]
	v_mov_b32_e32 v75, v73
	v_pk_add_f32 v[52:53], v[78:79], v[52:53]
	v_pk_add_f32 v[26:27], v[26:27], v[56:57]
	v_mul_f32_e32 v25, v8, v8
	v_mul_f32_e32 v80, v9, v9
	v_mul_f32_e32 v70, v17, v17
	v_mul_f32_e32 v76, v19, v19
	v_mov_b32_e32 v55, v81
	v_mov_b32_e32 v59, v82
	v_pk_add_f32 v[56:57], v[60:61], v[66:67]
	v_pk_add_f32 v[60:61], v[62:63], v[74:75]
	v_pk_add_f32 v[52:53], v[52:53], v[52:53] op_sel:[0,1] op_sel_hi:[1,0]
	v_pk_add_f32 v[26:27], v[26:27], v[26:27] op_sel:[0,1] op_sel_hi:[1,0]
	v_mul_f32_e32 v83, v0, v0
	v_mul_f32_e32 v84, v1, v1
	v_mul_f32_e32 v85, v2, v2
	v_mul_f32_e32 v86, v3, v3
	v_pk_fma_f32 v[72:73], v[16:17], v[16:17], v[70:71] op_sel_hi:[1,1,0]
	v_pk_fma_f32 v[76:77], v[18:19], v[18:19], v[76:77] op_sel_hi:[1,1,0]
	v_pk_add_f32 v[54:55], v[54:55], v[58:59]
	v_pk_add_f32 v[56:57], v[56:57], v[56:57] op_sel:[0,1] op_sel_hi:[1,0]
	v_pk_add_f32 v[58:59], v[60:61], v[60:61] op_sel:[0,1] op_sel_hi:[1,0]
	v_mov_b32_e32 v53, v25
	v_mov_b32_e32 v27, v80
	v_mov_b32_e32 v73, v85
	v_mov_b32_e32 v77, v86
	v_mov_b32_e32 v57, v83
	v_mov_b32_e32 v59, v84
	v_pk_add_f32 v[26:27], v[52:53], v[26:27]
	v_pk_add_f32 v[60:61], v[72:73], v[76:77]
	v_pk_add_f32 v[52:53], v[56:57], v[58:59]
	v_pk_add_f32 v[26:27], v[26:27], v[54:55]
	v_pk_add_f32 v[52:53], v[52:53], v[60:61]
	v_add_f32_e32 v25, v26, v27
	v_add_f32_e32 v26, v52, v53
	ds_bpermute_b32 v27, v71, v25
	ds_bpermute_b32 v52, v71, v26
	v_xor_b32_e32 v79, 8, v24
	v_xor_b32_e32 v81, 16, v24
	v_xor_b32_e32 v80, 32, v24
	s_waitcnt lgkmcnt(0)
	v_add_f32_e32 v25, v25, v27
	v_add_f32_e32 v26, v26, v52
	ds_bpermute_b32 v27, v79, v25
	ds_bpermute_b32 v52, v79, v26
	v_xor_b32_e32 v78, 64, v24
	v_xor_b32_e32 v77, 0x80, v24
	v_lshl_add_u64 v[66:67], v[68:69], 0, s[12:13]
	s_waitcnt lgkmcnt(1)
	v_add_f32_e32 v25, v25, v27
	s_waitcnt lgkmcnt(0)
	v_add_f32_e32 v26, v26, v52
	ds_bpermute_b32 v27, v81, v25
	ds_bpermute_b32 v52, v81, v26
	global_load_dwordx4 v[60:63], v[66:67], off
	global_load_dwordx4 v[56:59], v[66:67], off offset:1024
	v_pk_mul_f32 v[82:83], v[48:49], v[48:49]
	v_mov_b32_e32 v75, 0x358637bd
	s_waitcnt lgkmcnt(1)
	v_add_f32_e32 v24, v25, v27
	s_waitcnt lgkmcnt(0)
	v_add_f32_e32 v25, v26, v52
	ds_bpermute_b32 v26, v80, v24
	ds_bpermute_b32 v27, v80, v25
	v_mov_b32_e32 v73, 0x260
	s_waitcnt lgkmcnt(1)
	v_add_f32_e32 v70, v24, v26
	ds_bpermute_b32 v74, v78, v70
	s_waitcnt lgkmcnt(1)
	v_add_f32_e32 v72, v25, v27
	ds_bpermute_b32 v76, v78, v72
	global_load_dwordx4 v[52:55], v[66:67], off offset:2048
	global_load_dwordx4 v[24:27], v[66:67], off offset:3072
	v_pk_mul_f32 v[66:67], v[50:51], v[50:51]
	s_waitcnt lgkmcnt(1)
	v_add_f32_e32 v70, v70, v74
	ds_bpermute_b32 v74, v77, v70
	s_waitcnt lgkmcnt(1)
	v_add_f32_e32 v72, v72, v76
	ds_bpermute_b32 v76, v77, v72
	v_pk_mov_b32 v[84:85], v[82:83], v[66:67] op_sel:[1,0]
	v_mov_b32_e32 v83, v67
	s_waitcnt lgkmcnt(1)
	v_add_f32_e32 v66, v70, v74
	v_fmamk_f32 v66, v66, 0x3a800000, v75
	v_mul_f32_e32 v70, 0x4f800000, v66
	v_cmp_gt_f32_e32 vcc, s14, v66
	s_waitcnt lgkmcnt(0)
	v_add_f32_e32 v67, v72, v76
	v_fmamk_f32 v67, v67, 0x3a800000, v75
	v_cndmask_b32_e32 v66, v66, v70, vcc
	v_sqrt_f32_e32 v70, v66
	v_mul_f32_e32 v72, 0x4f800000, v67
	v_cmp_gt_f32_e64 s[0:1], s14, v67
	v_add_u32_e32 v74, 1, v70
	s_nop 0
	v_cndmask_b32_e64 v72, v67, v72, s[0:1]
	v_add_u32_e32 v67, -1, v70
	v_fma_f32 v76, -v67, v70, v66
	v_fma_f32 v86, -v74, v70, v66
	v_cmp_ge_f32_e64 s[2:3], 0, v76
	v_sqrt_f32_e32 v89, v72
	s_waitcnt vmcnt(0)
	v_mul_f32_e32 v97, v27, v27
	v_cndmask_b32_e64 v67, v70, v67, s[2:3]
	v_cmp_lt_f32_e64 s[2:3], 0, v86
	s_nop 1
	v_cndmask_b32_e64 v67, v67, v74, s[2:3]
	v_mul_f32_e32 v70, 0x37800000, v67
	v_cndmask_b32_e32 v67, v67, v70, vcc
	v_cmp_class_f32_e32 vcc, v66, v73
	v_mul_f32_e32 v70, v4, v4
	s_nop 0
	v_cndmask_b32_e32 v74, v67, v66, vcc
	v_div_scale_f32 v76, s[2:3], v74, v74, 1.0
	v_rcp_f32_e32 v88, v76
	v_div_scale_f32 v90, vcc, 1.0, v74, 1.0
	v_fma_f32 v66, -v76, v88, 1.0
	v_fmac_f32_e32 v88, v66, v88
	v_pk_add_f32 v[66:67], v[84:85], v[82:83]
	v_pk_mul_f32 v[82:83], v[38:39], v[38:39]
	v_pk_mul_f32 v[84:85], v[36:37], v[36:37]
	v_pk_add_f32 v[66:67], v[66:67], v[66:67] op_sel:[0,1] op_sel_hi:[1,0]
	v_pk_mov_b32 v[86:87], v[84:85], v[82:83] op_sel:[1,0]
	v_mov_b32_e32 v85, v83
	v_pk_add_f32 v[82:83], v[86:87], v[84:85]
	v_mul_f32_e32 v84, v5, v5
	v_pk_add_f32 v[82:83], v[82:83], v[82:83] op_sel:[0,1] op_sel_hi:[1,0]
	v_mov_b32_e32 v67, v70
	v_mov_b32_e32 v83, v84
	v_mul_f32_e32 v70, v21, v21
	v_mul_f32_e32 v85, v6, v6
	v_pk_add_f32 v[66:67], v[66:67], v[82:83]
	v_pk_fma_f32 v[82:83], v[20:21], v[20:21], v[70:71] op_sel_hi:[1,1,0]
	v_mul_f32_e32 v70, v23, v23
	v_mul_f32_e32 v86, v7, v7
	v_mov_b32_e32 v83, v85
	v_pk_fma_f32 v[84:85], v[22:23], v[22:23], v[70:71] op_sel_hi:[1,1,0]
	v_mul_f32_e32 v91, v90, v88
	v_mov_b32_e32 v85, v86
	v_pk_add_f32 v[82:83], v[82:83], v[84:85]
	v_fma_f32 v92, -v76, v91, v90
	v_pk_add_f32 v[66:67], v[66:67], v[82:83]
	v_fmac_f32_e32 v91, v92, v88
	v_add_f32_e32 v66, v66, v67
	ds_bpermute_b32 v67, v71, v66
	v_fma_f32 v70, -v76, v91, v90
	v_add_u32_e32 v76, -1, v89
	v_fma_f32 v82, -v76, v89, v72
	v_cmp_ge_f32_e64 s[2:3], 0, v82
	s_waitcnt lgkmcnt(0)
	v_add_f32_e32 v66, v66, v67
	ds_bpermute_b32 v67, v79, v66
	v_add_u32_e32 v82, 1, v89
	v_fma_f32 v83, -v82, v89, v72
	v_cndmask_b32_e64 v76, v89, v76, s[2:3]
	v_cmp_lt_f32_e64 s[2:3], 0, v83
	s_waitcnt lgkmcnt(0)
	v_add_f32_e32 v66, v66, v67
	ds_bpermute_b32 v67, v81, v66
	v_cndmask_b32_e64 v76, v76, v82, s[2:3]
	v_mul_f32_e32 v82, 0x37800000, v76
	v_cndmask_b32_e64 v76, v76, v82, s[0:1]
	v_cmp_class_f32_e64 s[0:1], v72, v73
	s_waitcnt lgkmcnt(0)
	v_add_f32_e32 v66, v66, v67
	ds_bpermute_b32 v67, v80, v66
	v_cndmask_b32_e64 v72, v76, v72, s[0:1]
	v_div_scale_f32 v76, s[0:1], v72, v72, 1.0
	v_pk_mul_f32 v[82:83], v[60:61], v[60:61]
	s_waitcnt lgkmcnt(0)
	v_add_f32_e32 v66, v66, v67
	ds_bpermute_b32 v67, v78, v66
	v_div_fmas_f32 v70, v70, v88, v91
	v_mul_f32_e32 v90, v26, v26
	v_rcp_f32_e32 v92, v76
	v_div_fixup_f32 v70, v70, v74, 1.0
	s_waitcnt lgkmcnt(0)
	v_add_f32_e32 v66, v66, v67
	ds_bpermute_b32 v67, v77, v66
	v_fma_f32 v74, -v76, v92, 1.0
	v_fmac_f32_e32 v92, v74, v92
	v_div_scale_f32 v74, vcc, 1.0, v72, 1.0
	s_waitcnt lgkmcnt(0)
	v_add_f32_e32 v66, v66, v67
	v_fmamk_f32 v66, v66, 0x3a800000, v75
	v_mul_f32_e32 v67, 0x4f800000, v66
	v_cmp_gt_f32_e64 s[0:1], s14, v66
	v_mul_f32_e32 v93, v74, v92
	v_fma_f32 v94, -v76, v93, v74
	v_cndmask_b32_e64 v95, v66, v67, s[0:1]
	v_pk_mul_f32 v[66:67], v[62:63], v[62:63]
	v_sqrt_f32_e32 v96, v95
	v_pk_mov_b32 v[84:85], v[82:83], v[66:67] op_sel:[1,0]
	v_mov_b32_e32 v83, v67
	v_pk_add_f32 v[66:67], v[84:85], v[82:83]
	v_pk_mul_f32 v[82:83], v[58:59], v[58:59]
	v_pk_mul_f32 v[84:85], v[56:57], v[56:57]
	v_pk_add_f32 v[66:67], v[66:67], v[66:67] op_sel:[0,1] op_sel_hi:[1,0]
	v_pk_mov_b32 v[86:87], v[84:85], v[82:83] op_sel:[1,0]
	v_mov_b32_e32 v85, v83
	v_pk_add_f32 v[82:83], v[86:87], v[84:85]
	v_mul_f32_e32 v84, v24, v24
	v_mul_f32_e32 v85, v25, v25
	v_pk_add_f32 v[82:83], v[82:83], v[82:83] op_sel:[0,1] op_sel_hi:[1,0]
	v_mov_b32_e32 v67, v84
	v_mov_b32_e32 v83, v85
	v_pk_add_f32 v[86:87], v[66:67], v[82:83]
	v_mul_f32_e32 v66, v53, v53
	v_pk_fma_f32 v[88:89], v[52:53], v[52:53], v[66:67] op_sel_hi:[1,1,0]
	v_mul_f32_e32 v66, v55, v55
	v_mov_b32_e32 v89, v90
	v_pk_fma_f32 v[90:91], v[54:55], v[54:55], v[66:67] op_sel_hi:[1,1,0]
	v_lshl_add_u64 v[66:67], s[4:5], 0, v[64:65]
	global_load_dwordx4 v[82:85], v[66:67], off
	v_mov_b32_e32 v91, v97
	v_pk_add_f32 v[88:89], v[88:89], v[90:91]
	v_fmac_f32_e32 v93, v94, v92
	v_pk_add_f32 v[86:87], v[86:87], v[88:89]
	v_fma_f32 v74, -v76, v93, v74
	v_add_f32_e32 v86, v86, v87
	ds_bpermute_b32 v87, v71, v86
	v_add_u32_e32 v76, -1, v96
	v_fma_f32 v88, -v76, v96, v95
	v_cmp_ge_f32_e64 s[2:3], 0, v88
	v_add_u32_e32 v88, 1, v96
	s_waitcnt lgkmcnt(0)
	v_add_f32_e32 v86, v86, v87
	ds_bpermute_b32 v87, v79, v86
	v_fma_f32 v89, -v88, v96, v95
	v_cndmask_b32_e64 v76, v96, v76, s[2:3]
	v_cmp_lt_f32_e64 s[2:3], 0, v89
	v_div_fmas_f32 v74, v74, v92, v93
	s_waitcnt lgkmcnt(0)
	v_add_f32_e32 v86, v86, v87
	ds_bpermute_b32 v87, v81, v86
	v_cndmask_b32_e64 v76, v76, v88, s[2:3]
	v_mul_f32_e32 v88, 0x37800000, v76
	v_cndmask_b32_e64 v76, v76, v88, s[0:1]
	v_cmp_class_f32_e64 s[0:1], v95, v73
	s_waitcnt lgkmcnt(0)
	v_add_f32_e32 v86, v86, v87
	ds_bpermute_b32 v87, v80, v86
	v_cndmask_b32_e64 v76, v76, v95, s[0:1]
	v_div_scale_f32 v88, s[0:1], v76, v76, 1.0
	v_rcp_f32_e32 v89, v88
	s_waitcnt lgkmcnt(0)
	v_add_f32_e32 v86, v86, v87
	ds_bpermute_b32 v87, v78, v86
	v_div_fixup_f32 v72, v74, v72, 1.0
	v_fma_f32 v74, -v88, v89, 1.0
	v_fmac_f32_e32 v89, v74, v89
	v_div_scale_f32 v74, vcc, 1.0, v76, 1.0
	s_waitcnt lgkmcnt(0)
	v_add_f32_e32 v86, v86, v87
	ds_bpermute_b32 v87, v77, v86
	v_mul_f32_e32 v90, v74, v89
	v_fma_f32 v91, -v88, v90, v74
	v_fmac_f32_e32 v90, v91, v89
	v_fma_f32 v74, -v88, v90, v74
	s_waitcnt lgkmcnt(0)
	v_add_f32_e32 v86, v86, v87
	v_fmamk_f32 v86, v86, 0x3a800000, v75
	v_mul_f32_e32 v87, 0x4f800000, v86
	v_cmp_gt_f32_e64 s[0:1], s14, v86
	v_div_fmas_f32 v74, v74, v89, v90
	v_div_fixup_f32 v74, v74, v76, 1.0
	v_cndmask_b32_e64 v86, v86, v87, s[0:1]
	v_sqrt_f32_e32 v87, v86
	v_pk_mul_f32 v[44:45], v[44:45], v[70:71] op_sel_hi:[1,0]
	v_pk_mul_f32 v[46:47], v[46:47], v[70:71] op_sel_hi:[1,0]
	v_pk_mul_f32 v[40:41], v[40:41], v[72:73] op_sel_hi:[1,0]
	v_add_u32_e32 v88, -1, v87
	v_fma_f32 v91, -v88, v87, v86
	v_cmp_ge_f32_e64 s[2:3], 0, v91
	v_add_u32_e32 v91, 1, v87
	v_pk_mul_f32 v[42:43], v[42:43], v[72:73] op_sel_hi:[1,0]
	v_cndmask_b32_e64 v88, v87, v88, s[2:3]
	v_fma_f32 v87, -v91, v87, v86
	v_cmp_lt_f32_e64 s[2:3], 0, v87
	v_pk_mul_f32 v[30:31], v[30:31], v[72:73] op_sel_hi:[1,0]
	v_pk_mul_f32 v[28:29], v[28:29], v[72:73] op_sel_hi:[1,0]
	v_cndmask_b32_e64 v87, v88, v91, s[2:3]
	v_mul_f32_e32 v88, 0x37800000, v87
	v_cndmask_b32_e64 v87, v87, v88, s[0:1]
	v_cmp_class_f32_e64 s[0:1], v86, v73
	v_pk_mul_f32 v[34:35], v[34:35], v[70:71] op_sel_hi:[1,0]
	v_pk_mul_f32 v[32:33], v[32:33], v[70:71] op_sel_hi:[1,0]
	v_cndmask_b32_e64 v86, v87, v86, s[0:1]
	v_div_scale_f32 v87, s[0:1], v86, v86, 1.0
	v_rcp_f32_e32 v88, v87
	s_add_u32 s0, s44, s10
	s_addc_u32 s1, s45, s11
	v_pk_mul_f32 v[18:19], v[18:19], v[72:73] op_sel_hi:[1,0]
	v_fma_f32 v76, -v87, v88, 1.0
	v_fmac_f32_e32 v88, v76, v88
	v_div_scale_f32 v76, vcc, 1.0, v86, 1.0
	v_mul_f32_e32 v89, v76, v88
	v_fma_f32 v90, -v87, v89, v76
	v_fmac_f32_e32 v89, v90, v88
	v_fma_f32 v76, -v87, v89, v76
	v_div_fmas_f32 v76, v76, v88, v89
	v_div_fixup_f32 v76, v76, v86, 1.0
	s_waitcnt vmcnt(0)
	v_pk_mul_f32 v[86:87], v[44:45], v[82:83]
	v_lshl_add_u64 v[44:45], s[0:1], 0, v[64:65]
	s_add_u32 s0, s44, s8
	s_addc_u32 s1, s45, s9
	v_pk_mul_f32 v[88:89], v[46:47], v[84:85]
	v_pk_mul_f32 v[42:43], v[42:43], v[84:85]
	v_pk_mul_f32 v[40:41], v[40:41], v[82:83]
	v_lshl_add_u64 v[46:47], s[0:1], 0, v[64:65]
	s_add_u32 s0, s44, s6
	global_store_dwordx4 v[46:47], v[40:43], off nt
	s_addc_u32 s1, s45, s7
	global_store_dwordx4 v[44:45], v[86:89], off nt
	v_pk_mul_f32 v[40:41], v[48:49], v[74:75] op_sel_hi:[1,0]
	v_pk_mul_f32 v[42:43], v[50:51], v[74:75] op_sel_hi:[1,0]
	v_pk_mul_f32 v[40:41], v[82:83], v[40:41]
	v_pk_mul_f32 v[42:43], v[84:85], v[42:43]
	v_lshl_add_u64 v[48:49], s[0:1], 0, v[64:65]
	s_add_u32 s0, s44, s12
	global_store_dwordx4 v[48:49], v[40:43], off nt
	s_addc_u32 s1, s45, s13
	v_lshl_add_u64 v[50:51], s[0:1], 0, v[64:65]
	v_pk_mul_f32 v[40:41], v[60:61], v[76:77] op_sel_hi:[1,0]
	v_pk_mul_f32 v[42:43], v[62:63], v[76:77] op_sel_hi:[1,0]
	v_pk_mul_f32 v[40:41], v[82:83], v[40:41]
	v_pk_mul_f32 v[42:43], v[84:85], v[42:43]
	global_store_dwordx4 v[50:51], v[40:43], off nt
	s_nop 1
	v_mov_b64_e32 v[40:41], v[108:109]
	v_mov_b64_e32 v[42:43], v[110:111]
	v_readlane_b32 s0, v251, 47
	v_readlane_b32 s1, v251, 48
	s_lshl_b64 s[4:5], s[0:1], 12
	v_pk_mul_f32 v[60:61], v[12:13], v[70:71] op_sel_hi:[1,0]
	v_pk_mul_f32 v[16:17], v[16:17], v[72:73] op_sel_hi:[1,0]
	v_readlane_b32 s0, v251, 51
	v_readlane_b32 s1, v251, 52
	s_lshl_b64 s[6:7], s[0:1], 12
	v_pk_mul_f32 v[2:3], v[2:3], v[72:73] op_sel_hi:[1,0]
	v_pk_mul_f32 v[0:1], v[0:1], v[72:73] op_sel_hi:[1,0]
	v_readlane_b32 s0, v251, 55
	v_readlane_b32 s1, v251, 56
	s_lshl_b64 s[8:9], s[0:1], 12
	v_readlane_b32 s10, v251, 23
	v_readlane_b32 s11, v251, 24
	s_nop 0
	v_pk_mul_f32 v[28:29], v[28:29], v[40:41]
	v_pk_mul_f32 v[30:31], v[30:31], v[42:43]
	global_store_dwordx4 v[46:47], v[28:31], off offset:1024 nt
	v_pk_mul_f32 v[32:33], v[32:33], v[40:41]
	v_pk_mul_f32 v[34:35], v[34:35], v[42:43]
	v_pk_mul_f32 v[30:31], v[38:39], v[74:75] op_sel_hi:[1,0]
	v_pk_mul_f32 v[28:29], v[36:37], v[74:75] op_sel_hi:[1,0]
	v_pk_mul_f32 v[30:31], v[30:31], v[42:43]
	v_pk_mul_f32 v[28:29], v[28:29], v[40:41]
	global_store_dwordx4 v[48:49], v[28:31], off offset:1024 nt
	global_store_dwordx4 v[44:45], v[32:35], off offset:1024 nt
	s_nop 0
	v_pk_mul_f32 v[30:31], v[58:59], v[76:77] op_sel_hi:[1,0]
	v_pk_mul_f32 v[28:29], v[56:57], v[76:77] op_sel_hi:[1,0]
	v_pk_mul_f32 v[30:31], v[42:43], v[30:31]
	v_pk_mul_f32 v[28:29], v[40:41], v[28:29]
	global_store_dwordx4 v[50:51], v[28:31], off offset:1024 nt
	global_load_dwordx4 v[40:43], v[66:67], off offset:2048
	v_lshl_add_u64 v[56:57], v[68:69], 0, s[4:5]
	global_load_dwordx4 v[36:39], v[56:57], off
	global_load_dwordx4 v[32:35], v[56:57], off offset:1024
	v_pk_mul_f32 v[58:59], v[14:15], v[70:71] op_sel_hi:[1,0]
	global_load_dwordx4 v[28:31], v[56:57], off offset:2048
	global_load_dwordx4 v[12:15], v[56:57], off offset:3072
	s_waitcnt vmcnt(4)
	v_pk_mul_f32 v[16:17], v[16:17], v[40:41]
	v_pk_mul_f32 v[18:19], v[18:19], v[42:43]
	global_store_dwordx4 v[46:47], v[16:19], off offset:2048 nt
	v_pk_mul_f32 v[56:57], v[60:61], v[40:41]
	v_pk_mul_f32 v[58:59], v[58:59], v[42:43]
	v_pk_mul_f32 v[18:19], v[22:23], v[74:75] op_sel_hi:[1,0]
	v_pk_mul_f32 v[16:17], v[20:21], v[74:75] op_sel_hi:[1,0]
	v_pk_mul_f32 v[18:19], v[18:19], v[42:43]
	v_pk_mul_f32 v[16:17], v[16:17], v[40:41]
	global_store_dwordx4 v[48:49], v[16:19], off offset:2048 nt
	global_store_dwordx4 v[44:45], v[56:59], off offset:2048 nt
	v_pk_mul_f32 v[60:61], v[8:9], v[70:71] op_sel_hi:[1,0]
	v_pk_mul_f32 v[18:19], v[54:55], v[76:77] op_sel_hi:[1,0]
	v_pk_mul_f32 v[16:17], v[52:53], v[76:77] op_sel_hi:[1,0]
	v_pk_mul_f32 v[18:19], v[18:19], v[42:43]
	v_pk_mul_f32 v[16:17], v[16:17], v[40:41]
	global_store_dwordx4 v[50:51], v[16:19], off offset:2048 nt
	global_load_dwordx4 v[52:55], v[66:67], off offset:3072
	v_lshl_add_u64 v[56:57], v[68:69], 0, s[6:7]
	global_load_dwordx4 v[40:43], v[56:57], off
	global_load_dwordx4 v[20:23], v[56:57], off offset:1024
	v_pk_mul_f32 v[58:59], v[10:11], v[70:71] op_sel_hi:[1,0]
	global_load_dwordx4 v[16:19], v[56:57], off offset:2048
	global_load_dwordx4 v[8:11], v[56:57], off offset:3072
	s_waitcnt vmcnt(12)
	v_pk_mul_f32 v[56:57], v[38:39], v[38:39]
	v_pk_mul_f32 v[62:63], v[36:37], v[36:37]
	s_waitcnt vmcnt(9)
	v_mul_f32_e32 v70, v12, v12
	v_pk_mov_b32 v[82:83], v[62:63], v[56:57] op_sel:[1,0]
	v_mov_b32_e32 v63, v57
	v_pk_add_f32 v[56:57], v[82:83], v[62:63]
	v_pk_mul_f32 v[62:63], v[34:35], v[34:35]
	v_pk_mul_f32 v[82:83], v[32:33], v[32:33]
	v_pk_add_f32 v[56:57], v[56:57], v[56:57] op_sel:[0,1] op_sel_hi:[1,0]
	v_pk_mov_b32 v[84:85], v[82:83], v[62:63] op_sel:[1,0]
	v_mov_b32_e32 v83, v63
	v_pk_add_f32 v[62:63], v[84:85], v[82:83]
	v_mul_f32_e32 v82, v13, v13
	v_pk_add_f32 v[62:63], v[62:63], v[62:63] op_sel:[0,1] op_sel_hi:[1,0]
	v_mov_b32_e32 v57, v70
	v_mov_b32_e32 v63, v82
	v_pk_add_f32 v[56:57], v[56:57], v[62:63]
	v_mul_f32_e32 v62, v29, v29
	v_mul_f32_e32 v83, v14, v14
	v_pk_fma_f32 v[62:63], v[28:29], v[28:29], v[62:63] op_sel_hi:[1,1,0]
	v_mul_f32_e32 v70, v31, v31
	v_mul_f32_e32 v84, v15, v15
	v_mov_b32_e32 v63, v83
	v_pk_fma_f32 v[82:83], v[30:31], v[30:31], v[70:71] op_sel_hi:[1,1,0]
	s_waitcnt vmcnt(4)
	v_pk_mul_f32 v[58:59], v[58:59], v[54:55]
	v_mov_b32_e32 v83, v84
	v_pk_add_f32 v[62:63], v[62:63], v[82:83]
	v_pk_mul_f32 v[0:1], v[0:1], v[52:53]
	v_pk_add_f32 v[56:57], v[56:57], v[62:63]
	v_pk_mul_f32 v[2:3], v[2:3], v[54:55]
	v_add_f32_e32 v62, v56, v57
	ds_bpermute_b32 v63, v71, v62
	v_pk_mul_f32 v[56:57], v[60:61], v[52:53]
	global_store_dwordx4 v[44:45], v[56:59], off offset:3072 nt
	global_store_dwordx4 v[46:47], v[0:3], off offset:3072 nt
	s_waitcnt lgkmcnt(0)
	v_add_f32_e32 v44, v62, v63
	ds_bpermute_b32 v45, v79, v44
	v_pk_mul_f32 v[0:1], v[4:5], v[74:75] op_sel_hi:[1,0]
	v_pk_mul_f32 v[2:3], v[6:7], v[74:75] op_sel_hi:[1,0]
	v_pk_mul_f32 v[0:1], v[0:1], v[52:53]
	v_pk_mul_f32 v[2:3], v[2:3], v[54:55]
	s_waitcnt lgkmcnt(0)
	v_add_f32_e32 v44, v44, v45
	ds_bpermute_b32 v45, v81, v44
	global_store_dwordx4 v[48:49], v[0:3], off offset:3072 nt
	s_waitcnt lgkmcnt(0)
	v_add_f32_e32 v4, v44, v45
	ds_bpermute_b32 v5, v80, v4
	v_pk_mul_f32 v[2:3], v[26:27], v[76:77] op_sel_hi:[1,0]
	v_pk_mul_f32 v[0:1], v[24:25], v[76:77] op_sel_hi:[1,0]
	v_pk_mul_f32 v[2:3], v[2:3], v[54:55]
	v_pk_mul_f32 v[0:1], v[0:1], v[52:53]
	s_waitcnt lgkmcnt(0)
	v_add_f32_e32 v4, v4, v5
	ds_bpermute_b32 v5, v78, v4
	global_store_dwordx4 v[50:51], v[0:3], off offset:3072 nt
	v_lshl_add_u64 v[44:45], v[68:69], 0, s[8:9]
	v_lshl_add_u64 v[68:69], v[68:69], 0, s[10:11]
	s_waitcnt lgkmcnt(0)
	v_add_f32_e32 v46, v4, v5
	global_load_dwordx4 v[48:51], v[44:45], off
	global_load_dwordx4 v[24:27], v[44:45], off offset:1024
	global_load_dwordx4 v[4:7], v[44:45], off offset:2048
	global_load_dwordx4 v[0:3], v[44:45], off offset:3072
	ds_bpermute_b32 v47, v77, v46
	global_load_dwordx4 v[60:63], v[68:69], off
	global_load_dwordx4 v[56:59], v[68:69], off offset:1024
	s_waitcnt lgkmcnt(0)
	v_add_f32_e32 v44, v46, v47
	v_fmamk_f32 v44, v44, 0x3a800000, v75
	v_mul_f32_e32 v45, 0x4f800000, v44
	v_cmp_gt_f32_e32 vcc, s14, v44
	s_waitcnt vmcnt(13)
	v_pk_mul_f32 v[46:47], v[40:41], v[40:41]
	v_cndmask_b32_e32 v70, v44, v45, vcc
	v_pk_mul_f32 v[44:45], v[42:43], v[42:43]
	v_sqrt_f32_e32 v72, v70
	v_pk_mov_b32 v[52:53], v[46:47], v[44:45] op_sel:[1,0]
	v_mov_b32_e32 v47, v45
	v_pk_add_f32 v[44:45], v[52:53], v[46:47]
	s_waitcnt vmcnt(12)
	v_pk_mul_f32 v[46:47], v[22:23], v[22:23]
	v_pk_mul_f32 v[52:53], v[20:21], v[20:21]
	v_pk_add_f32 v[44:45], v[44:45], v[44:45] op_sel:[0,1] op_sel_hi:[1,0]
	v_pk_mov_b32 v[54:55], v[52:53], v[46:47] op_sel:[1,0]
	v_mov_b32_e32 v53, v47
	v_pk_add_f32 v[46:47], v[54:55], v[52:53]
	s_waitcnt vmcnt(10)
	v_mul_f32_e32 v52, v8, v8
	v_mul_f32_e32 v53, v9, v9
	v_pk_add_f32 v[46:47], v[46:47], v[46:47] op_sel:[0,1] op_sel_hi:[1,0]
	v_mov_b32_e32 v45, v52
	v_mov_b32_e32 v47, v53
	v_pk_add_f32 v[44:45], v[44:45], v[46:47]
	v_mul_f32_e32 v46, v17, v17
	v_mul_f32_e32 v52, v19, v19
	v_mul_f32_e32 v54, v10, v10
	v_mul_f32_e32 v55, v11, v11
	v_pk_fma_f32 v[46:47], v[16:17], v[16:17], v[46:47] op_sel_hi:[1,1,0]
	v_pk_fma_f32 v[52:53], v[18:19], v[18:19], v[52:53] op_sel_hi:[1,1,0]
	v_mov_b32_e32 v47, v54
	v_mov_b32_e32 v53, v55
	v_pk_add_f32 v[46:47], v[46:47], v[52:53]
	s_nop 0
	v_pk_add_f32 v[44:45], v[44:45], v[46:47]
	v_add_u32_e32 v46, -1, v72
	v_add_f32_e32 v44, v44, v45
	ds_bpermute_b32 v45, v71, v44
	v_fma_f32 v47, -v46, v72, v70
	v_cmp_ge_f32_e64 s[0:1], 0, v47
	v_add_u32_e32 v47, 1, v72
	v_fma_f32 v52, -v47, v72, v70
	s_waitcnt lgkmcnt(0)
	v_add_f32_e32 v44, v44, v45
	ds_bpermute_b32 v45, v79, v44
	v_cndmask_b32_e64 v46, v72, v46, s[0:1]
	v_cmp_lt_f32_e64 s[0:1], 0, v52
	s_waitcnt lgkmcnt(0)
	v_add_f32_e32 v44, v44, v45
	ds_bpermute_b32 v45, v81, v44
	v_cndmask_b32_e64 v46, v46, v47, s[0:1]
	v_mul_f32_e32 v47, 0x37800000, v46
	v_cndmask_b32_e32 v46, v46, v47, vcc
	v_cmp_class_f32_e32 vcc, v70, v73
	s_waitcnt lgkmcnt(0)
	v_add_f32_e32 v44, v44, v45
	ds_bpermute_b32 v45, v80, v44
	v_cndmask_b32_e32 v72, v46, v70, vcc
	v_div_scale_f32 v74, s[0:1], v72, v72, 1.0
	v_rcp_f32_e32 v76, v74
	s_waitcnt lgkmcnt(0)
	v_add_f32_e32 v70, v44, v45
	global_load_dwordx4 v[52:55], v[68:69], off offset:2048
	global_load_dwordx4 v[44:47], v[68:69], off offset:3072
	ds_bpermute_b32 v82, v78, v70
	v_fma_f32 v68, -v74, v76, 1.0
	v_fmac_f32_e32 v76, v68, v76
	v_div_scale_f32 v88, vcc, 1.0, v72, 1.0
	s_waitcnt lgkmcnt(0)
	v_add_f32_e32 v68, v70, v82
	ds_bpermute_b32 v69, v77, v68
	v_mul_f32_e32 v89, v88, v76
	v_fma_f32 v90, -v74, v89, v88
	s_waitcnt vmcnt(7)
	v_pk_mul_f32 v[82:83], v[48:49], v[48:49]
	v_fmac_f32_e32 v89, v90, v76
	s_waitcnt lgkmcnt(0)
	v_add_f32_e32 v68, v68, v69
	v_fmamk_f32 v68, v68, 0x3a800000, v75
	v_mul_f32_e32 v69, 0x4f800000, v68
	v_cmp_gt_f32_e64 s[0:1], s14, v68
	s_waitcnt vmcnt(4)
	v_mul_f32_e32 v70, v0, v0
	s_waitcnt vmcnt(0)
	v_mul_f32_e32 v90, v46, v46
	v_cndmask_b32_e64 v91, v68, v69, s[0:1]
	v_pk_mul_f32 v[68:69], v[50:51], v[50:51]
	v_sqrt_f32_e32 v92, v91
	v_pk_mov_b32 v[84:85], v[82:83], v[68:69] op_sel:[1,0]
	v_mov_b32_e32 v83, v69
	v_pk_add_f32 v[68:69], v[84:85], v[82:83]
	v_pk_mul_f32 v[82:83], v[26:27], v[26:27]
	v_pk_mul_f32 v[84:85], v[24:25], v[24:25]
	v_pk_add_f32 v[68:69], v[68:69], v[68:69] op_sel:[0,1] op_sel_hi:[1,0]
	v_pk_mov_b32 v[86:87], v[84:85], v[82:83] op_sel:[1,0]
	v_mov_b32_e32 v85, v83
	v_pk_add_f32 v[82:83], v[86:87], v[84:85]
	v_mul_f32_e32 v84, v1, v1
	v_pk_add_f32 v[82:83], v[82:83], v[82:83] op_sel:[0,1] op_sel_hi:[1,0]
	v_mov_b32_e32 v69, v70
	v_mov_b32_e32 v83, v84
	v_mul_f32_e32 v70, v5, v5
	v_mul_f32_e32 v85, v2, v2
	v_pk_add_f32 v[68:69], v[68:69], v[82:83]
	v_pk_fma_f32 v[82:83], v[4:5], v[4:5], v[70:71] op_sel_hi:[1,1,0]
	v_mul_f32_e32 v70, v7, v7
	v_mul_f32_e32 v86, v3, v3
	v_mov_b32_e32 v83, v85
	v_pk_fma_f32 v[84:85], v[6:7], v[6:7], v[70:71] op_sel_hi:[1,1,0]
	v_fma_f32 v70, -v74, v89, v88
	v_mov_b32_e32 v85, v86
	v_pk_add_f32 v[82:83], v[82:83], v[84:85]
	v_add_u32_e32 v74, -1, v92
	v_pk_add_f32 v[68:69], v[68:69], v[82:83]
	v_fma_f32 v82, -v74, v92, v91
	v_add_f32_e32 v68, v68, v69
	ds_bpermute_b32 v69, v71, v68
	v_cmp_ge_f32_e64 s[2:3], 0, v82
	v_add_u32_e32 v82, 1, v92
	v_fma_f32 v83, -v82, v92, v91
	v_cndmask_b32_e64 v74, v92, v74, s[2:3]
	s_waitcnt lgkmcnt(0)
	v_add_f32_e32 v68, v68, v69
	ds_bpermute_b32 v69, v79, v68
	v_cmp_lt_f32_e64 s[2:3], 0, v83
	v_pk_mul_f32 v[84:85], v[60:61], v[60:61]
	v_mul_f32_e32 v96, v47, v47
	v_cndmask_b32_e64 v74, v74, v82, s[2:3]
	s_waitcnt lgkmcnt(0)
	v_add_f32_e32 v68, v68, v69
	ds_bpermute_b32 v69, v81, v68
	v_mul_f32_e32 v82, 0x37800000, v74
	v_cndmask_b32_e64 v74, v74, v82, s[0:1]
	v_cmp_class_f32_e64 s[0:1], v91, v73
	s_waitcnt lgkmcnt(0)
	v_add_f32_e32 v68, v68, v69
	ds_bpermute_b32 v69, v80, v68
	v_cndmask_b32_e64 v74, v74, v91, s[0:1]
	v_div_scale_f32 v92, s[0:1], v74, v74, 1.0
	v_rcp_f32_e32 v93, v92
	s_waitcnt lgkmcnt(0)
	v_add_f32_e32 v69, v68, v69
	ds_bpermute_b32 v82, v78, v69
	v_div_fmas_f32 v68, v70, v76, v89
	v_fma_f32 v70, -v92, v93, 1.0
	v_fmac_f32_e32 v93, v70, v93
	v_div_fixup_f32 v68, v68, v72, 1.0
	s_waitcnt lgkmcnt(0)
	v_add_f32_e32 v69, v69, v82
	ds_bpermute_b32 v70, v77, v69
	v_pk_mul_f32 v[82:83], v[62:63], v[62:63]
	v_div_scale_f32 v72, vcc, 1.0, v74, 1.0
	v_pk_mov_b32 v[86:87], v[84:85], v[82:83] op_sel:[1,0]
	v_mov_b32_e32 v85, v83
	s_waitcnt lgkmcnt(0)
	v_add_f32_e32 v69, v69, v70
	v_pk_add_f32 v[82:83], v[86:87], v[84:85]
	v_pk_mul_f32 v[84:85], v[58:59], v[58:59]
	v_pk_mul_f32 v[86:87], v[56:57], v[56:57]
	v_fmamk_f32 v69, v69, 0x3a800000, v75
	v_pk_mov_b32 v[88:89], v[86:87], v[84:85] op_sel:[1,0]
	v_mov_b32_e32 v87, v85
	v_mul_f32_e32 v70, 0x4f800000, v69
	v_cmp_gt_f32_e64 s[0:1], s14, v69
	v_pk_add_f32 v[84:85], v[88:89], v[86:87]
	v_mul_f32_e32 v86, v45, v45
	v_cndmask_b32_e64 v69, v69, v70, s[0:1]
	v_mul_f32_e32 v70, v44, v44
	v_pk_add_f32 v[82:83], v[82:83], v[82:83] op_sel:[0,1] op_sel_hi:[1,0]
	v_pk_add_f32 v[84:85], v[84:85], v[84:85] op_sel:[0,1] op_sel_hi:[1,0]
	v_mov_b32_e32 v83, v70
	v_mov_b32_e32 v85, v86
	v_pk_add_f32 v[86:87], v[82:83], v[84:85]
	global_load_dwordx4 v[82:85], v[66:67], off
	v_mul_f32_e32 v70, v53, v53
	v_pk_fma_f32 v[88:89], v[52:53], v[52:53], v[70:71] op_sel_hi:[1,1,0]
	v_mul_f32_e32 v70, v55, v55
	v_mov_b32_e32 v89, v90
	v_pk_fma_f32 v[90:91], v[54:55], v[54:55], v[70:71] op_sel_hi:[1,1,0]
	v_sqrt_f32_e32 v95, v69
	v_mov_b32_e32 v91, v96
	v_pk_add_f32 v[88:89], v[88:89], v[90:91]
	v_mul_f32_e32 v76, v72, v93
	v_pk_add_f32 v[86:87], v[86:87], v[88:89]
	v_fma_f32 v94, -v92, v76, v72
	v_add_f32_e32 v70, v86, v87
	ds_bpermute_b32 v71, v71, v70
	v_add_u32_e32 v86, -1, v95
	v_fma_f32 v87, -v86, v95, v69
	v_cmp_ge_f32_e64 s[2:3], 0, v87
	v_fmac_f32_e32 v76, v94, v93
	s_waitcnt lgkmcnt(0)
	v_add_f32_e32 v70, v70, v71
	ds_bpermute_b32 v71, v79, v70
	v_cndmask_b32_e64 v79, v95, v86, s[2:3]
	v_add_u32_e32 v86, 1, v95
	v_fma_f32 v72, -v92, v76, v72
	v_fma_f32 v87, -v86, v95, v69
	s_waitcnt lgkmcnt(0)
	v_add_f32_e32 v70, v70, v71
	ds_bpermute_b32 v71, v81, v70
	v_cmp_lt_f32_e64 s[2:3], 0, v87
	s_waitcnt lgkmcnt(0)
	v_add_f32_e32 v70, v70, v71
	ds_bpermute_b32 v71, v80, v70
	v_cndmask_b32_e64 v79, v79, v86, s[2:3]
	v_mul_f32_e32 v81, 0x37800000, v79
	v_cndmask_b32_e64 v79, v79, v81, s[0:1]
	v_cmp_class_f32_e64 s[0:1], v69, v73
	s_waitcnt lgkmcnt(0)
	v_add_f32_e32 v71, v70, v71
	ds_bpermute_b32 v78, v78, v71
	v_div_fmas_f32 v70, v72, v93, v76
	v_div_fixup_f32 v70, v70, v74, 1.0
	v_cndmask_b32_e64 v69, v79, v69, s[0:1]
	v_div_scale_f32 v79, s[0:1], v69, v69, 1.0
	s_waitcnt lgkmcnt(0)
	v_add_f32_e32 v71, v71, v78
	ds_bpermute_b32 v74, v77, v71
	v_rcp_f32_e32 v80, v79
	s_waitcnt lgkmcnt(0)
	v_add_f32_e32 v71, v71, v74
	v_fmac_f32_e32 v75, 0x3a800000, v71
	v_mul_f32_e32 v71, 0x4f800000, v75
	v_cmp_gt_f32_e64 s[0:1], s14, v75
	v_fma_f32 v72, -v79, v80, 1.0
	v_fmac_f32_e32 v80, v72, v80
	v_cndmask_b32_e64 v71, v75, v71, s[0:1]
	v_sqrt_f32_e32 v74, v71
	v_div_scale_f32 v72, vcc, 1.0, v69, 1.0
	v_mul_f32_e32 v76, v72, v80
	v_fma_f32 v75, -v79, v76, v72
	v_fmac_f32_e32 v76, v75, v80
	v_add_u32_e32 v75, -1, v74
	v_fma_f32 v77, -v75, v74, v71
	v_cmp_ge_f32_e64 s[2:3], 0, v77
	v_add_u32_e32 v77, 1, v74
	v_fma_f32 v72, -v79, v76, v72
	v_cndmask_b32_e64 v75, v74, v75, s[2:3]
	v_fma_f32 v74, -v77, v74, v71
	v_cmp_lt_f32_e64 s[2:3], 0, v74
	v_div_fmas_f32 v72, v72, v80, v76
	v_div_fixup_f32 v72, v72, v69, 1.0
	v_cndmask_b32_e64 v74, v75, v77, s[2:3]
	v_mul_f32_e32 v75, 0x37800000, v74
	v_cndmask_b32_e64 v74, v74, v75, s[0:1]
	v_cmp_class_f32_e64 s[0:1], v71, v73
	s_nop 1
	v_cndmask_b32_e64 v71, v74, v71, s[0:1]
	v_div_scale_f32 v73, s[0:1], v71, v71, 1.0
	v_rcp_f32_e32 v74, v73
	s_add_u32 s0, s44, s4
	s_addc_u32 s1, s45, s5
	v_pk_mul_f32 v[22:23], v[22:23], v[70:71] op_sel_hi:[1,0]
	v_fma_f32 v69, -v73, v74, 1.0
	v_fmac_f32_e32 v74, v69, v74
	v_div_scale_f32 v69, vcc, 1.0, v71, 1.0
	v_mul_f32_e32 v75, v69, v74
	v_fma_f32 v76, -v73, v75, v69
	v_fmac_f32_e32 v75, v76, v74
	v_fma_f32 v69, -v73, v75, v69
	v_div_fmas_f32 v69, v69, v74, v75
	v_pk_mul_f32 v[36:37], v[36:37], v[68:69] op_sel_hi:[1,0]
	v_pk_mul_f32 v[38:39], v[38:39], v[68:69] op_sel_hi:[1,0]
	s_waitcnt vmcnt(0)
	v_pk_mul_f32 v[36:37], v[36:37], v[82:83]
	v_pk_mul_f32 v[38:39], v[38:39], v[84:85]
	v_lshl_add_u64 v[76:77], s[0:1], 0, v[64:65]
	s_add_u32 s0, s44, s6
	global_store_dwordx4 v[76:77], v[36:39], off nt
	s_addc_u32 s1, s45, s7
	v_div_fixup_f32 v74, v69, v71, 1.0
	v_pk_mul_f32 v[36:37], v[40:41], v[70:71] op_sel_hi:[1,0]
	v_pk_mul_f32 v[38:39], v[42:43], v[70:71] op_sel_hi:[1,0]
	v_pk_mul_f32 v[36:37], v[36:37], v[82:83]
	v_pk_mul_f32 v[38:39], v[38:39], v[84:85]
	v_lshl_add_u64 v[40:41], s[0:1], 0, v[64:65]
	s_add_u32 s0, s44, s8
	global_store_dwordx4 v[40:41], v[36:39], off nt
	s_addc_u32 s1, s45, s9
	v_lshl_add_u64 v[42:43], s[0:1], 0, v[64:65]
	v_pk_mul_f32 v[36:37], v[48:49], v[72:73] op_sel_hi:[1,0]
	v_pk_mul_f32 v[38:39], v[50:51], v[72:73] op_sel_hi:[1,0]
	v_pk_mul_f32 v[36:37], v[82:83], v[36:37]
	v_pk_mul_f32 v[38:39], v[84:85], v[38:39]
	s_add_u32 s0, s44, s10
	global_store_dwordx4 v[42:43], v[36:39], off nt
	s_addc_u32 s1, s45, s11
	v_lshl_add_u64 v[48:49], s[0:1], 0, v[64:65]
	v_pk_mul_f32 v[36:37], v[60:61], v[74:75] op_sel_hi:[1,0]
	v_pk_mul_f32 v[38:39], v[62:63], v[74:75] op_sel_hi:[1,0]
	v_pk_mul_f32 v[36:37], v[82:83], v[36:37]
	v_pk_mul_f32 v[38:39], v[84:85], v[38:39]
	global_store_dwordx4 v[48:49], v[36:39], off nt
	s_nop 1
	v_mov_b64_e32 v[36:37], v[108:109]
	v_mov_b64_e32 v[38:39], v[110:111]
	v_pk_mul_f32 v[20:21], v[20:21], v[70:71] op_sel_hi:[1,0]
	v_pk_mul_f32 v[34:35], v[34:35], v[68:69] op_sel_hi:[1,0]
	v_pk_mul_f32 v[32:33], v[32:33], v[68:69] op_sel_hi:[1,0]
	v_pk_mul_f32 v[6:7], v[6:7], v[72:73] op_sel_hi:[1,0]
	v_pk_mul_f32 v[4:5], v[4:5], v[72:73] op_sel_hi:[1,0]
	v_pk_mul_f32 v[18:19], v[18:19], v[70:71] op_sel_hi:[1,0]
	v_pk_mul_f32 v[16:17], v[16:17], v[70:71] op_sel_hi:[1,0]
	v_pk_mul_f32 v[2:3], v[2:3], v[72:73] op_sel_hi:[1,0]
	v_pk_mul_f32 v[0:1], v[0:1], v[72:73] op_sel_hi:[1,0]
	v_pk_mul_f32 v[14:15], v[14:15], v[68:69] op_sel_hi:[1,0]
	v_pk_mul_f32 v[12:13], v[12:13], v[68:69] op_sel_hi:[1,0]
	v_pk_mul_f32 v[10:11], v[10:11], v[70:71] op_sel_hi:[1,0]
	v_pk_mul_f32 v[8:9], v[8:9], v[70:71] op_sel_hi:[1,0]
	s_nop 0
	v_pk_mul_f32 v[20:21], v[20:21], v[36:37]
	v_pk_mul_f32 v[22:23], v[22:23], v[38:39]
	global_store_dwordx4 v[40:41], v[20:23], off offset:1024 nt
	v_pk_mul_f32 v[32:33], v[32:33], v[36:37]
	v_pk_mul_f32 v[34:35], v[34:35], v[38:39]
	v_pk_mul_f32 v[22:23], v[26:27], v[72:73] op_sel_hi:[1,0]
	v_pk_mul_f32 v[20:21], v[24:25], v[72:73] op_sel_hi:[1,0]
	v_pk_mul_f32 v[22:23], v[22:23], v[38:39]
	v_pk_mul_f32 v[20:21], v[20:21], v[36:37]
	global_store_dwordx4 v[42:43], v[20:23], off offset:1024 nt
	global_store_dwordx4 v[76:77], v[32:35], off offset:1024 nt
	v_pk_mul_f32 v[26:27], v[30:31], v[68:69] op_sel_hi:[1,0]
	v_pk_mul_f32 v[22:23], v[58:59], v[74:75] op_sel_hi:[1,0]
	v_pk_mul_f32 v[20:21], v[56:57], v[74:75] op_sel_hi:[1,0]
	v_pk_mul_f32 v[22:23], v[38:39], v[22:23]
	v_pk_mul_f32 v[20:21], v[36:37], v[20:21]
	global_store_dwordx4 v[48:49], v[20:23], off offset:1024 nt
	s_nop 1
	v_mov_b64_e32 v[20:21], v[112:113]
	v_mov_b64_e32 v[22:23], v[114:115]
	v_pk_mul_f32 v[24:25], v[28:29], v[68:69] op_sel_hi:[1,0]
	s_nop 0
	v_pk_mul_f32 v[4:5], v[4:5], v[20:21]
	v_pk_mul_f32 v[6:7], v[6:7], v[22:23]
	global_store_dwordx4 v[42:43], v[4:7], off offset:2048 nt
	v_pk_mul_f32 v[24:25], v[24:25], v[20:21]
	v_pk_mul_f32 v[26:27], v[26:27], v[22:23]
	v_pk_mul_f32 v[6:7], v[54:55], v[74:75] op_sel_hi:[1,0]
	v_pk_mul_f32 v[4:5], v[52:53], v[74:75] op_sel_hi:[1,0]
	v_pk_mul_f32 v[16:17], v[16:17], v[20:21]
	v_pk_mul_f32 v[18:19], v[18:19], v[22:23]
	v_pk_mul_f32 v[4:5], v[4:5], v[20:21]
	v_pk_mul_f32 v[6:7], v[6:7], v[22:23]
	global_store_dwordx4 v[76:77], v[24:27], off offset:2048 nt
	global_store_dwordx4 v[40:41], v[16:19], off offset:2048 nt
	global_store_dwordx4 v[48:49], v[4:7], off offset:2048 nt
	s_nop 1
	v_mov_b64_e32 v[4:5], v[116:117]
	v_mov_b64_e32 v[6:7], v[118:119]
	s_nop 0
	v_pk_mul_f32 v[0:1], v[0:1], v[4:5]
	v_pk_mul_f32 v[2:3], v[2:3], v[6:7]
	global_store_dwordx4 v[42:43], v[0:3], off offset:3072 nt
	v_pk_mul_f32 v[12:13], v[12:13], v[4:5]
	v_pk_mul_f32 v[14:15], v[14:15], v[6:7]
	v_pk_mul_f32 v[2:3], v[46:47], v[74:75] op_sel_hi:[1,0]
	v_pk_mul_f32 v[0:1], v[44:45], v[74:75] op_sel_hi:[1,0]
	v_pk_mul_f32 v[8:9], v[8:9], v[4:5]
	v_pk_mul_f32 v[10:11], v[10:11], v[6:7]
	v_pk_mul_f32 v[0:1], v[0:1], v[4:5]
	v_pk_mul_f32 v[2:3], v[2:3], v[6:7]
	global_store_dwordx4 v[76:77], v[12:15], off offset:3072 nt
	global_store_dwordx4 v[40:41], v[8:11], off offset:3072 nt
	global_store_dwordx4 v[48:49], v[0:3], off offset:3072 nt
	s_endpgm
